# NSA tile loops: PV V-fragment waits counted per MFMA (lgkmcnt 6/4/2/0) instead of a full LDS drain per d-block
# baseline (speedup 1.0000x reference)
; #define SBAR() __builtin_amdgcn_sched_barrier(0)
; template <int OFF> DI s16x4 tr_read(int vb) { s16x4 r; asm volatile("ds_read_b64_tr_b16 %0, %1 offset:%2" : "=&v"(r) : "v"(vb), "i"(OFF) : "memory"); return r; }
; template <int D, int D0> DI void pv_one(f32x16& od, int vb, bf16x8 pa0, bf16x8 pa1, bf16x8 pa2, bf16x8 pa3) {
;     const s16x4 l0 = tr_read<v_rd_off<D>(D0, 0, 0)>(vb), h0 = tr_read<v_rd_off<D>(D0, 0, 1)>(vb), l1 = tr_read<v_rd_off<D>(D0, 1, 0)>(vb), h1 = tr_read<v_rd_off<D>(D0, 1, 1)>(vb);
;     const s16x4 l2 = tr_read<v_rd_off<D>(D0, 2, 0)>(vb), h2 = tr_read<v_rd_off<D>(D0, 2, 1)>(vb), l3 = tr_read<v_rd_off<D>(D0, 3, 0)>(vb), h3 = tr_read<v_rd_off<D>(D0, 3, 1)>(vb);
;     asm volatile("s_waitcnt lgkmcnt(0)" ::: "memory"); SBAR();
;     ...
;     od = __builtin_amdgcn_mfma_f32_32x32x16_bf16(pa0, PK(l0, h0), od, 0, 0, 0);
;     od = __builtin_amdgcn_mfma_f32_32x32x16_bf16(pa1, PK(l1, h1), od, 0, 0, 0);
;     od = __builtin_amdgcn_mfma_f32_32x32x16_bf16(pa2, PK(l2, h2), od, 0, 0, 0);
;     od = __builtin_amdgcn_mfma_f32_32x32x16_bf16(pa3, PK(l3, h3), od, 0, 0, 0);
;     ...
; }
; template <int D> DI void pv_all(f32x16* o, int vb, bf16x8 pa0, bf16x8 pa1, bf16x8 pa2, bf16x8 pa3) {
;     pv_one<D, 0>(o[0], vb, pa0, pa1, pa2, pa3); pv_one<D, 1>(o[1], vb, pa0, pa1, pa2, pa3);
;     if constexpr (D == 128) { pv_one<D, 2>(o[2], vb, pa0, pa1, pa2, pa3); pv_one<D, 3>(o[3], vb, pa0, pa1, pa2, pa3); }
; template <int D, bool PIPE, class Seq, class MaskF, class KX>
; DI void run_tiles(Core<D>& c, char* kv, float* ws, const bf16_t* Kg0, const bf16_t* Vg0, int pitch, const Seq& seq, const MaskF& mk, const KX& kx, int tid_, int lane_) {
;     ...
;             if (e1) { kx.apply(sk, t1, tid); stg_wrK<D>(sk, kv + (buf ^ 1) * KB, tid); stg_wrV<D>(sv, kv + 2 * KB + (buf ^ 1) * KB, tid); }
.Lpv_fast_sel:
	s_waitcnt lgkmcnt(6)
	s_nop 0
	v_mfma_f32_32x32x16_bf16 v[50:65], v[66:69], v[84:87], v[50:65]
	ds_read_b64_tr_b16 v[84:85], v96 offset:0x200
	ds_read_b64_tr_b16 v[86:87], v96 offset:0xa00
	s_waitcnt lgkmcnt(6)
	v_mfma_f32_32x32x16_bf16 v[50:65], v[70:73], v[88:91], v[50:65]
	ds_read_b64_tr_b16 v[88:89], v96 offset:0x1200
	ds_read_b64_tr_b16 v[90:91], v96 offset:0x1a00
	s_waitcnt lgkmcnt(6)
	v_mfma_f32_32x32x16_bf16 v[50:65], v[74:77], v[92:95], v[50:65]
	ds_read_b64_tr_b16 v[92:93], v96 offset:0x2200
	ds_read_b64_tr_b16 v[94:95], v96 offset:0x2a00
	s_waitcnt lgkmcnt(6)
	v_mfma_f32_32x32x16_bf16 v[50:65], v[78:81], v[186:189], v[50:65]
	ds_read_b64_tr_b16 v[186:187], v96 offset:0x3200
	ds_read_b64_tr_b16 v[188:189], v96 offset:0x3a00
	s_waitcnt lgkmcnt(6)
	v_mfma_f32_32x32x16_bf16 v[34:49], v[66:69], v[84:87], v[34:49]
	ds_read_b64_tr_b16 v[84:85], v96 offset:0x400
	ds_read_b64_tr_b16 v[86:87], v96 offset:0xc00
	s_waitcnt lgkmcnt(6)
	v_mfma_f32_32x32x16_bf16 v[34:49], v[70:73], v[88:91], v[34:49]
	ds_read_b64_tr_b16 v[88:89], v96 offset:0x1400
	ds_read_b64_tr_b16 v[90:91], v96 offset:0x1c00
	s_waitcnt lgkmcnt(6)
	v_mfma_f32_32x32x16_bf16 v[34:49], v[74:77], v[92:95], v[34:49]
	ds_read_b64_tr_b16 v[92:93], v96 offset:0x2400
	ds_read_b64_tr_b16 v[94:95], v96 offset:0x2c00
	s_waitcnt lgkmcnt(6)
	v_mfma_f32_32x32x16_bf16 v[34:49], v[78:81], v[186:189], v[34:49]
	ds_read_b64_tr_b16 v[186:187], v96 offset:0x3400
	ds_read_b64_tr_b16 v[188:189], v96 offset:0x3c00
	s_waitcnt lgkmcnt(6)
	v_mfma_f32_32x32x16_bf16 v[18:33], v[66:69], v[84:87], v[18:33]
	ds_read_b64_tr_b16 v[84:85], v96 offset:0x600
	ds_read_b64_tr_b16 v[86:87], v96 offset:0xe00
	s_waitcnt lgkmcnt(6)
	v_mfma_f32_32x32x16_bf16 v[18:33], v[70:73], v[88:91], v[18:33]
	ds_read_b64_tr_b16 v[88:89], v96 offset:0x1600
	ds_read_b64_tr_b16 v[90:91], v96 offset:0x1e00
	s_waitcnt lgkmcnt(6)
	v_mfma_f32_32x32x16_bf16 v[18:33], v[74:77], v[92:95], v[18:33]
	ds_read_b64_tr_b16 v[92:93], v96 offset:0x2600
	ds_read_b64_tr_b16 v[94:95], v96 offset:0x2e00
	s_waitcnt lgkmcnt(6)
	v_mfma_f32_32x32x16_bf16 v[18:33], v[78:81], v[186:189], v[18:33]
	ds_read_b64_tr_b16 v[186:187], v96 offset:0x3600
	ds_read_b64_tr_b16 v[188:189], v96 offset:0x3e00
	s_waitcnt lgkmcnt(6)
	v_mfma_f32_32x32x16_bf16 v[2:17], v[66:69], v[84:87], v[2:17]
	v_cndmask_b32_e64 v67, 0, 1, s[52:53]
	s_andn2_b64 vcc, exec, s[52:53]
	s_waitcnt lgkmcnt(4)
	v_mfma_f32_32x32x16_bf16 v[2:17], v[70:73], v[88:91], v[2:17]
	s_waitcnt lgkmcnt(2)
	v_mfma_f32_32x32x16_bf16 v[2:17], v[74:77], v[92:95], v[2:17]
	s_waitcnt lgkmcnt(0)
	v_mfma_f32_32x32x16_bf16 v[2:17], v[78:81], v[186:189], v[2:17]
	s_cbranch_vccnz .LBB0_873
	s_xor_b32 s14, s61, 0x4000
	s_add_i32 s14, s14, 0
	v_add_u32_e32 v69, s14, v208
	s_mov_b32 s59, s60
	v_add_u32_e32 v66, s14, v215
	v_add_u32_e32 v68, s14, v214
	s_waitcnt vmcnt(3)
	ds_write_b128 v69, v[98:101]
	s_waitcnt vmcnt(2)
	ds_write_b128 v69, v[102:105] offset:8192
	s_waitcnt vmcnt(1)
	ds_write_b128 v68, v[106:109] offset:32768
	s_waitcnt vmcnt(0)
	ds_write_b128 v66, v[144:147] offset:32768

; #define SBAR() __builtin_amdgcn_sched_barrier(0)
; template <int OFF> DI s16x4 tr_read(int vb) { s16x4 r; asm volatile("ds_read_b64_tr_b16 %0, %1 offset:%2" : "=&v"(r) : "v"(vb), "i"(OFF) : "memory"); return r; }
; template <int D, int D0> DI void pv_one(f32x16& od, int vb, bf16x8 pa0, bf16x8 pa1, bf16x8 pa2, bf16x8 pa3) {
;     const s16x4 l0 = tr_read<v_rd_off<D>(D0, 0, 0)>(vb), h0 = tr_read<v_rd_off<D>(D0, 0, 1)>(vb), l1 = tr_read<v_rd_off<D>(D0, 1, 0)>(vb), h1 = tr_read<v_rd_off<D>(D0, 1, 1)>(vb);
;     const s16x4 l2 = tr_read<v_rd_off<D>(D0, 2, 0)>(vb), h2 = tr_read<v_rd_off<D>(D0, 2, 1)>(vb), l3 = tr_read<v_rd_off<D>(D0, 3, 0)>(vb), h3 = tr_read<v_rd_off<D>(D0, 3, 1)>(vb);
;     asm volatile("s_waitcnt lgkmcnt(0)" ::: "memory"); SBAR();
;     ...
;     od = __builtin_amdgcn_mfma_f32_32x32x16_bf16(pa0, PK(l0, h0), od, 0, 0, 0);
;     od = __builtin_amdgcn_mfma_f32_32x32x16_bf16(pa1, PK(l1, h1), od, 0, 0, 0);
;     od = __builtin_amdgcn_mfma_f32_32x32x16_bf16(pa2, PK(l2, h2), od, 0, 0, 0);
;     od = __builtin_amdgcn_mfma_f32_32x32x16_bf16(pa3, PK(l3, h3), od, 0, 0, 0);
;     ...
; }
; template <int D> DI void pv_all(f32x16* o, int vb, bf16x8 pa0, bf16x8 pa1, bf16x8 pa2, bf16x8 pa3) {
;     pv_one<D, 0>(o[0], vb, pa0, pa1, pa2, pa3); pv_one<D, 1>(o[1], vb, pa0, pa1, pa2, pa3);
;     if constexpr (D == 128) { pv_one<D, 2>(o[2], vb, pa0, pa1, pa2, pa3); pv_one<D, 3>(o[3], vb, pa0, pa1, pa2, pa3); }
; template <int D, bool PIPE, class Seq, class MaskF, class KX>
; DI void run_tiles(Core<D>& c, char* kv, float* ws, const bf16_t* Kg0, const bf16_t* Vg0, int pitch, const Seq& seq, const MaskF& mk, const KX& kx, int tid_, int lane_) {
;     ...
;             if (e1) { kx.apply(sk, t1, tid); stg_wrK<D>(sk, kv + (buf ^ 1) * KB, tid); stg_wrV<D>(sv, kv + 2 * KB + (buf ^ 1) * KB, tid); }
.Lpv_fast_win:
	s_waitcnt lgkmcnt(6)
	s_nop 0
	v_mfma_f32_32x32x16_bf16 v[50:65], v[66:69], v[84:87], v[50:65]
	ds_read_b64_tr_b16 v[84:85], v96 offset:0x200
	ds_read_b64_tr_b16 v[86:87], v96 offset:0xa00
	s_waitcnt lgkmcnt(6)
	v_mfma_f32_32x32x16_bf16 v[50:65], v[70:73], v[88:91], v[50:65]
	ds_read_b64_tr_b16 v[88:89], v96 offset:0x1200
	ds_read_b64_tr_b16 v[90:91], v96 offset:0x1a00
	s_waitcnt lgkmcnt(6)
	v_mfma_f32_32x32x16_bf16 v[50:65], v[74:77], v[92:95], v[50:65]
	ds_read_b64_tr_b16 v[92:93], v96 offset:0x2200
	ds_read_b64_tr_b16 v[94:95], v96 offset:0x2a00
	s_waitcnt lgkmcnt(6)
	v_mfma_f32_32x32x16_bf16 v[50:65], v[78:81], v[186:189], v[50:65]
	ds_read_b64_tr_b16 v[186:187], v96 offset:0x3200
	ds_read_b64_tr_b16 v[188:189], v96 offset:0x3a00
	s_waitcnt lgkmcnt(6)
	v_mfma_f32_32x32x16_bf16 v[34:49], v[66:69], v[84:87], v[34:49]
	ds_read_b64_tr_b16 v[84:85], v96 offset:0x400
	ds_read_b64_tr_b16 v[86:87], v96 offset:0xc00
	s_waitcnt lgkmcnt(6)
	v_mfma_f32_32x32x16_bf16 v[34:49], v[70:73], v[88:91], v[34:49]
	ds_read_b64_tr_b16 v[88:89], v96 offset:0x1400
	ds_read_b64_tr_b16 v[90:91], v96 offset:0x1c00
	s_waitcnt lgkmcnt(6)
	v_mfma_f32_32x32x16_bf16 v[34:49], v[74:77], v[92:95], v[34:49]
	ds_read_b64_tr_b16 v[92:93], v96 offset:0x2400
	ds_read_b64_tr_b16 v[94:95], v96 offset:0x2c00
	s_waitcnt lgkmcnt(6)
	v_mfma_f32_32x32x16_bf16 v[34:49], v[78:81], v[186:189], v[34:49]
	ds_read_b64_tr_b16 v[186:187], v96 offset:0x3400
	ds_read_b64_tr_b16 v[188:189], v96 offset:0x3c00
	s_waitcnt lgkmcnt(6)
	v_mfma_f32_32x32x16_bf16 v[18:33], v[66:69], v[84:87], v[18:33]
	ds_read_b64_tr_b16 v[84:85], v96 offset:0x600
	ds_read_b64_tr_b16 v[86:87], v96 offset:0xe00
	s_waitcnt lgkmcnt(6)
	v_mfma_f32_32x32x16_bf16 v[18:33], v[70:73], v[88:91], v[18:33]
	ds_read_b64_tr_b16 v[88:89], v96 offset:0x1600
	ds_read_b64_tr_b16 v[90:91], v96 offset:0x1e00
	s_waitcnt lgkmcnt(6)
	v_mfma_f32_32x32x16_bf16 v[18:33], v[74:77], v[92:95], v[18:33]
	ds_read_b64_tr_b16 v[92:93], v96 offset:0x2600
	ds_read_b64_tr_b16 v[94:95], v96 offset:0x2e00
	s_waitcnt lgkmcnt(6)
	v_mfma_f32_32x32x16_bf16 v[18:33], v[78:81], v[186:189], v[18:33]
	ds_read_b64_tr_b16 v[186:187], v96 offset:0x3600
	ds_read_b64_tr_b16 v[188:189], v96 offset:0x3e00
	s_waitcnt lgkmcnt(6)
	v_mfma_f32_32x32x16_bf16 v[2:17], v[66:69], v[84:87], v[2:17]
	v_cndmask_b32_e64 v66, 0, 1, s[2:3]
	s_andn2_b64 vcc, exec, s[2:3]
	s_waitcnt lgkmcnt(4)
	v_mfma_f32_32x32x16_bf16 v[2:17], v[70:73], v[88:91], v[2:17]
	s_waitcnt lgkmcnt(2)
	v_mfma_f32_32x32x16_bf16 v[2:17], v[74:77], v[92:95], v[2:17]
	s_waitcnt lgkmcnt(0)
	v_mfma_f32_32x32x16_bf16 v[2:17], v[78:81], v[186:189], v[2:17]
	s_cbranch_vccnz .LBB0_894
	s_xor_b32 s2, s93, 0x4000
	s_add_i32 s2, s2, 0
	v_add_u32_e32 v69, s2, v205
	s_mov_b32 s92, s88
	v_add_u32_e32 v67, s2, v213
	v_add_u32_e32 v68, s2, v212
	s_waitcnt vmcnt(3)
	ds_write_b128 v69, v[98:101]
	s_waitcnt vmcnt(2)
	ds_write_b128 v69, v[102:105] offset:8192
	s_waitcnt vmcnt(1)
	ds_write_b128 v68, v[106:109] offset:32768
	s_waitcnt vmcnt(0)
	ds_write_b128 v67, v[144:147] offset:32768
